# attention step: waves 4-7 start each step 9x64 cycles after waves 0-3 (s_sleep after the step barrier) so the two waves of a SIMD are out of phase
# speedup vs baseline: 1.0062x; 1.0021x over previous
.Lattn_noskip:
	s_cmp_lt_u32 s67, 4
	s_cbranch_scc1 .Lattn_nosleep
	s_sleep 9
